# grid barrier: acquire-side buffer_inv issued at arrival (under the arrival atomic's round trip) instead of after the release is seen
# speedup vs baseline: 1.0261x; 1.0261x over previous
.LBB0_333:
	s_add_i32 s74, s74, 1
	s_cmp_ge_i32 s74, s75
	s_mov_b64 s[0:1], -1
	s_cbranch_scc1 .LBB0_10
	v_readlane_b32 s4, v253, 38
	v_readlane_b32 s5, v253, 39
	s_and_b64 vcc, exec, s[4:5]
	s_cbranch_vccz .LBB0_389
	s_waitcnt vmcnt(0)
	s_waitcnt vmcnt(0) lgkmcnt(0)
	s_barrier
	s_mov_b64 s[0:1], exec
	v_readlane_b32 s4, v253, 2
	v_readlane_b32 s5, v253, 3
	s_and_b64 s[4:5], s[0:1], s[4:5]
	s_mov_b64 exec, s[4:5]
	s_cbranch_execz .LBB0_388
	v_mov_b32_e32 v0, 0x13800
	s_waitcnt vmcnt(0) expcnt(0) lgkmcnt(0)
	buffer_inv sc1
	ds_read_b32 v3, v0
	v_mov_b32_e32 v0, 0x13804
	ds_read_b32 v2, v0
	s_waitcnt lgkmcnt(1)
	v_cmp_ne_u32_e32 vcc, 0, v3
	s_cbranch_vccnz .LBB0_351
	s_mov_b32 s4, 1
	s_branch .LBB0_339

.LBB0_367:
	s_or_b64 exec, exec, s[22:23]
	s_waitcnt vmcnt(0)
	s_waitcnt vmcnt(0)

.LBB0_385:
	s_or_b64 exec, exec, s[20:21]
	s_mov_b64 s[20:21], exec
	v_mbcnt_lo_u32_b32 v0, s20, 0
	v_mbcnt_hi_u32_b32 v0, s21, v0
	v_cmp_eq_u32_e32 vcc, 0, v0
	s_waitcnt vmcnt(0)
	s_and_saveexec_b64 s[22:23], vcc
	s_cbranch_execz .LBB0_387
	s_bcnt1_i32_b64 s4, s[20:21]
	v_mov_b32_e32 v0, s4
	v_readlane_b32 s4, v254, 44
	v_readlane_b32 s5, v254, 45
	s_nop 4
	global_atomic_add v1, v0, s[4:5]
